# weight conversion: column-masked tiles issue their 32 loads together (one wait) instead of 32 serialized masked load->vmcnt(0) round trips
# speedup vs baseline: 1.0222x; 1.0079x over previous
.Lcw0_entry:
	v_mov_b32_e32 v84, 0
	v_mov_b32_e32 v85, 0
	v_mov_b32_e32 v86, 0
	v_mov_b32_e32 v87, 0
	v_mov_b32_e32 v88, 0
	v_mov_b32_e32 v89, 0
	v_mov_b32_e32 v90, 0
	v_mov_b32_e32 v91, 0
	v_mov_b32_e32 v92, 0
	v_mov_b32_e32 v93, 0
	v_mov_b32_e32 v94, 0
	v_mov_b32_e32 v95, 0
	v_mov_b32_e32 v96, 0
	v_mov_b32_e32 v97, 0
	v_mov_b32_e32 v98, 0
	v_mov_b32_e32 v99, 0
	v_mov_b32_e32 v100, 0
	v_mov_b32_e32 v101, 0
	v_mov_b32_e32 v102, 0
	v_mov_b32_e32 v103, 0
	v_mov_b32_e32 v104, 0
	v_mov_b32_e32 v105, 0
	v_mov_b32_e32 v106, 0
	v_mov_b32_e32 v107, 0
	v_mov_b32_e32 v108, 0
	v_mov_b32_e32 v109, 0
	v_mov_b32_e32 v110, 0
	v_mov_b32_e32 v111, 0
	v_mov_b32_e32 v112, 0
	v_mov_b32_e32 v113, 0
	v_mov_b32_e32 v114, 0
	v_mov_b32_e32 v115, 0
	s_and_saveexec_b64 s[28:29], vcc
	s_cbranch_execz .Lcw0_skip
	v_mov_b32_e32 v11, v3
	v_mad_i64_i32 v[22:23], s[36:37], v11, s34, v[12:13]
	global_load_dword v84, v[22:23], off
	v_add_u32_e32 v11, 2, v3
	v_mad_i64_i32 v[22:23], s[36:37], v11, s34, v[12:13]
	global_load_dword v85, v[22:23], off
	v_add_u32_e32 v11, 4, v3
	v_mad_i64_i32 v[22:23], s[36:37], v11, s34, v[12:13]
	global_load_dword v86, v[22:23], off
	v_add_u32_e32 v11, 6, v3
	v_mad_i64_i32 v[22:23], s[36:37], v11, s34, v[12:13]
	global_load_dword v87, v[22:23], off
	v_add_u32_e32 v11, 8, v3
	v_mad_i64_i32 v[22:23], s[36:37], v11, s34, v[12:13]
	global_load_dword v88, v[22:23], off
	v_add_u32_e32 v11, 10, v3
	v_mad_i64_i32 v[22:23], s[36:37], v11, s34, v[12:13]
	global_load_dword v89, v[22:23], off
	v_add_u32_e32 v11, 12, v3
	v_mad_i64_i32 v[22:23], s[36:37], v11, s34, v[12:13]
	global_load_dword v90, v[22:23], off
	v_add_u32_e32 v11, 14, v3
	v_mad_i64_i32 v[22:23], s[36:37], v11, s34, v[12:13]
	global_load_dword v91, v[22:23], off
	v_add_u32_e32 v11, 16, v3
	v_mad_i64_i32 v[22:23], s[36:37], v11, s34, v[12:13]
	global_load_dword v92, v[22:23], off
	v_add_u32_e32 v11, 18, v3
	v_mad_i64_i32 v[22:23], s[36:37], v11, s34, v[12:13]
	global_load_dword v93, v[22:23], off
	v_add_u32_e32 v11, 20, v3
	v_mad_i64_i32 v[22:23], s[36:37], v11, s34, v[12:13]
	global_load_dword v94, v[22:23], off
	v_add_u32_e32 v11, 22, v3
	v_mad_i64_i32 v[22:23], s[36:37], v11, s34, v[12:13]
	global_load_dword v95, v[22:23], off
	v_add_u32_e32 v11, 24, v3
	v_mad_i64_i32 v[22:23], s[36:37], v11, s34, v[12:13]
	global_load_dword v96, v[22:23], off
	v_add_u32_e32 v11, 26, v3
	v_mad_i64_i32 v[22:23], s[36:37], v11, s34, v[12:13]
	global_load_dword v97, v[22:23], off
	v_add_u32_e32 v11, 28, v3
	v_mad_i64_i32 v[22:23], s[36:37], v11, s34, v[12:13]
	global_load_dword v98, v[22:23], off
	v_add_u32_e32 v11, 30, v3
	v_mad_i64_i32 v[22:23], s[36:37], v11, s34, v[12:13]
	global_load_dword v99, v[22:23], off
	v_add_u32_e32 v11, 32, v3
	v_mad_i64_i32 v[22:23], s[36:37], v11, s34, v[12:13]
	global_load_dword v100, v[22:23], off
	v_add_u32_e32 v11, 34, v3
	v_mad_i64_i32 v[22:23], s[36:37], v11, s34, v[12:13]
	global_load_dword v101, v[22:23], off
	v_add_u32_e32 v11, 36, v3
	v_mad_i64_i32 v[22:23], s[36:37], v11, s34, v[12:13]
	global_load_dword v102, v[22:23], off
	v_add_u32_e32 v11, 38, v3
	v_mad_i64_i32 v[22:23], s[36:37], v11, s34, v[12:13]
	global_load_dword v103, v[22:23], off
	v_add_u32_e32 v11, 40, v3
	v_mad_i64_i32 v[22:23], s[36:37], v11, s34, v[12:13]
	global_load_dword v104, v[22:23], off
	v_add_u32_e32 v11, 42, v3
	v_mad_i64_i32 v[22:23], s[36:37], v11, s34, v[12:13]
	global_load_dword v105, v[22:23], off
	v_add_u32_e32 v11, 44, v3
	v_mad_i64_i32 v[22:23], s[36:37], v11, s34, v[12:13]
	global_load_dword v106, v[22:23], off
	v_add_u32_e32 v11, 46, v3
	v_mad_i64_i32 v[22:23], s[36:37], v11, s34, v[12:13]
	global_load_dword v107, v[22:23], off
	v_add_u32_e32 v11, 48, v3
	v_mad_i64_i32 v[22:23], s[36:37], v11, s34, v[12:13]
	global_load_dword v108, v[22:23], off
	v_add_u32_e32 v11, 50, v3
	v_mad_i64_i32 v[22:23], s[36:37], v11, s34, v[12:13]
	global_load_dword v109, v[22:23], off
	v_add_u32_e32 v11, 52, v3
	v_mad_i64_i32 v[22:23], s[36:37], v11, s34, v[12:13]
	global_load_dword v110, v[22:23], off
	v_add_u32_e32 v11, 54, v3
	v_mad_i64_i32 v[22:23], s[36:37], v11, s34, v[12:13]
	global_load_dword v111, v[22:23], off
	v_add_u32_e32 v11, 56, v3
	v_mad_i64_i32 v[22:23], s[36:37], v11, s34, v[12:13]
	global_load_dword v112, v[22:23], off
	v_add_u32_e32 v11, 58, v3
	v_mad_i64_i32 v[22:23], s[36:37], v11, s34, v[12:13]
	global_load_dword v113, v[22:23], off
	v_add_u32_e32 v11, 60, v3
	v_mad_i64_i32 v[22:23], s[36:37], v11, s34, v[12:13]
	global_load_dword v114, v[22:23], off
	v_add_u32_e32 v11, 62, v3
	v_mad_i64_i32 v[22:23], s[36:37], v11, s34, v[12:13]
	global_load_dword v115, v[22:23], off
.Lcw0_skip:
	s_or_b64 exec, exec, s[28:29]
	s_waitcnt vmcnt(0)
	ds_write_b32 v8, v84
	ds_write_b32 v8, v85 offset:264
	ds_write_b32 v8, v86 offset:528
	ds_write_b32 v8, v87 offset:792
	ds_write_b32 v8, v88 offset:1056
	ds_write_b32 v8, v89 offset:1320
	ds_write_b32 v8, v90 offset:1584
	ds_write_b32 v8, v91 offset:1848
	ds_write_b32 v8, v92 offset:2112
	ds_write_b32 v8, v93 offset:2376
	ds_write_b32 v8, v94 offset:2640
	ds_write_b32 v8, v95 offset:2904
	ds_write_b32 v8, v96 offset:3168
	ds_write_b32 v8, v97 offset:3432
	ds_write_b32 v8, v98 offset:3696
	ds_write_b32 v8, v99 offset:3960
	ds_write_b32 v8, v100 offset:4224
	ds_write_b32 v8, v101 offset:4488
	ds_write_b32 v8, v102 offset:4752
	ds_write_b32 v8, v103 offset:5016
	ds_write_b32 v8, v104 offset:5280
	ds_write_b32 v8, v105 offset:5544
	ds_write_b32 v8, v106 offset:5808
	ds_write_b32 v8, v107 offset:6072
	ds_write_b32 v8, v108 offset:6336
	ds_write_b32 v8, v109 offset:6600
	ds_write_b32 v8, v110 offset:6864
	ds_write_b32 v8, v111 offset:7128
	ds_write_b32 v8, v112 offset:7392
	ds_write_b32 v8, v113 offset:7656
	ds_write_b32 v8, v114 offset:7920
	ds_write_b32 v8, v115 offset:8184
	v_add_u32_e32 v8, 0x2100, v8
	s_mov_b32 s27, 64
	s_branch .LBB0_7

.Lcw1_entry:
	v_mov_b32_e32 v84, 0
	v_mov_b32_e32 v85, 0
	v_mov_b32_e32 v86, 0
	v_mov_b32_e32 v87, 0
	v_mov_b32_e32 v88, 0
	v_mov_b32_e32 v89, 0
	v_mov_b32_e32 v90, 0
	v_mov_b32_e32 v91, 0
	v_mov_b32_e32 v92, 0
	v_mov_b32_e32 v93, 0
	v_mov_b32_e32 v94, 0
	v_mov_b32_e32 v95, 0
	v_mov_b32_e32 v96, 0
	v_mov_b32_e32 v97, 0
	v_mov_b32_e32 v98, 0
	v_mov_b32_e32 v99, 0
	v_mov_b32_e32 v100, 0
	v_mov_b32_e32 v101, 0
	v_mov_b32_e32 v102, 0
	v_mov_b32_e32 v103, 0
	v_mov_b32_e32 v104, 0
	v_mov_b32_e32 v105, 0
	v_mov_b32_e32 v106, 0
	v_mov_b32_e32 v107, 0
	v_mov_b32_e32 v108, 0
	v_mov_b32_e32 v109, 0
	v_mov_b32_e32 v110, 0
	v_mov_b32_e32 v111, 0
	v_mov_b32_e32 v112, 0
	v_mov_b32_e32 v113, 0
	v_mov_b32_e32 v114, 0
	v_mov_b32_e32 v115, 0
	s_and_saveexec_b64 s[6:7], vcc
	s_cbranch_execz .Lcw1_skip
	v_mov_b32_e32 v10, v0
	v_mad_i64_i32 v[18:19], s[10:11], v10, s36, v[8:9]
	global_load_dword v84, v[18:19], off
	v_add_u32_e32 v10, 2, v0
	v_mad_i64_i32 v[18:19], s[10:11], v10, s36, v[8:9]
	global_load_dword v85, v[18:19], off
	v_add_u32_e32 v10, 4, v0
	v_mad_i64_i32 v[18:19], s[10:11], v10, s36, v[8:9]
	global_load_dword v86, v[18:19], off
	v_add_u32_e32 v10, 6, v0
	v_mad_i64_i32 v[18:19], s[10:11], v10, s36, v[8:9]
	global_load_dword v87, v[18:19], off
	v_add_u32_e32 v10, 8, v0
	v_mad_i64_i32 v[18:19], s[10:11], v10, s36, v[8:9]
	global_load_dword v88, v[18:19], off
	v_add_u32_e32 v10, 10, v0
	v_mad_i64_i32 v[18:19], s[10:11], v10, s36, v[8:9]
	global_load_dword v89, v[18:19], off
	v_add_u32_e32 v10, 12, v0
	v_mad_i64_i32 v[18:19], s[10:11], v10, s36, v[8:9]
	global_load_dword v90, v[18:19], off
	v_add_u32_e32 v10, 14, v0
	v_mad_i64_i32 v[18:19], s[10:11], v10, s36, v[8:9]
	global_load_dword v91, v[18:19], off
	v_add_u32_e32 v10, 16, v0
	v_mad_i64_i32 v[18:19], s[10:11], v10, s36, v[8:9]
	global_load_dword v92, v[18:19], off
	v_add_u32_e32 v10, 18, v0
	v_mad_i64_i32 v[18:19], s[10:11], v10, s36, v[8:9]
	global_load_dword v93, v[18:19], off
	v_add_u32_e32 v10, 20, v0
	v_mad_i64_i32 v[18:19], s[10:11], v10, s36, v[8:9]
	global_load_dword v94, v[18:19], off
	v_add_u32_e32 v10, 22, v0
	v_mad_i64_i32 v[18:19], s[10:11], v10, s36, v[8:9]
	global_load_dword v95, v[18:19], off
	v_add_u32_e32 v10, 24, v0
	v_mad_i64_i32 v[18:19], s[10:11], v10, s36, v[8:9]
	global_load_dword v96, v[18:19], off
	v_add_u32_e32 v10, 26, v0
	v_mad_i64_i32 v[18:19], s[10:11], v10, s36, v[8:9]
	global_load_dword v97, v[18:19], off
	v_add_u32_e32 v10, 28, v0
	v_mad_i64_i32 v[18:19], s[10:11], v10, s36, v[8:9]
	global_load_dword v98, v[18:19], off
	v_add_u32_e32 v10, 30, v0
	v_mad_i64_i32 v[18:19], s[10:11], v10, s36, v[8:9]
	global_load_dword v99, v[18:19], off
	v_add_u32_e32 v10, 32, v0
	v_mad_i64_i32 v[18:19], s[10:11], v10, s36, v[8:9]
	global_load_dword v100, v[18:19], off
	v_add_u32_e32 v10, 34, v0
	v_mad_i64_i32 v[18:19], s[10:11], v10, s36, v[8:9]
	global_load_dword v101, v[18:19], off
	v_add_u32_e32 v10, 36, v0
	v_mad_i64_i32 v[18:19], s[10:11], v10, s36, v[8:9]
	global_load_dword v102, v[18:19], off
	v_add_u32_e32 v10, 38, v0
	v_mad_i64_i32 v[18:19], s[10:11], v10, s36, v[8:9]
	global_load_dword v103, v[18:19], off
	v_add_u32_e32 v10, 40, v0
	v_mad_i64_i32 v[18:19], s[10:11], v10, s36, v[8:9]
	global_load_dword v104, v[18:19], off
	v_add_u32_e32 v10, 42, v0
	v_mad_i64_i32 v[18:19], s[10:11], v10, s36, v[8:9]
	global_load_dword v105, v[18:19], off
	v_add_u32_e32 v10, 44, v0
	v_mad_i64_i32 v[18:19], s[10:11], v10, s36, v[8:9]
	global_load_dword v106, v[18:19], off
	v_add_u32_e32 v10, 46, v0
	v_mad_i64_i32 v[18:19], s[10:11], v10, s36, v[8:9]
	global_load_dword v107, v[18:19], off
	v_add_u32_e32 v10, 48, v0
	v_mad_i64_i32 v[18:19], s[10:11], v10, s36, v[8:9]
	global_load_dword v108, v[18:19], off
	v_add_u32_e32 v10, 50, v0
	v_mad_i64_i32 v[18:19], s[10:11], v10, s36, v[8:9]
	global_load_dword v109, v[18:19], off
	v_add_u32_e32 v10, 52, v0
	v_mad_i64_i32 v[18:19], s[10:11], v10, s36, v[8:9]
	global_load_dword v110, v[18:19], off
	v_add_u32_e32 v10, 54, v0
	v_mad_i64_i32 v[18:19], s[10:11], v10, s36, v[8:9]
	global_load_dword v111, v[18:19], off
	v_add_u32_e32 v10, 56, v0
	v_mad_i64_i32 v[18:19], s[10:11], v10, s36, v[8:9]
	global_load_dword v112, v[18:19], off
	v_add_u32_e32 v10, 58, v0
	v_mad_i64_i32 v[18:19], s[10:11], v10, s36, v[8:9]
	global_load_dword v113, v[18:19], off
	v_add_u32_e32 v10, 60, v0
	v_mad_i64_i32 v[18:19], s[10:11], v10, s36, v[8:9]
	global_load_dword v114, v[18:19], off
	v_add_u32_e32 v10, 62, v0
	v_mad_i64_i32 v[18:19], s[10:11], v10, s36, v[8:9]
	global_load_dword v115, v[18:19], off
.Lcw1_skip:
	s_or_b64 exec, exec, s[6:7]
	s_waitcnt vmcnt(0)
	ds_write_b32 v5, v84
	ds_write_b32 v5, v85 offset:264
	ds_write_b32 v5, v86 offset:528
	ds_write_b32 v5, v87 offset:792
	ds_write_b32 v5, v88 offset:1056
	ds_write_b32 v5, v89 offset:1320
	ds_write_b32 v5, v90 offset:1584
	ds_write_b32 v5, v91 offset:1848
	ds_write_b32 v5, v92 offset:2112
	ds_write_b32 v5, v93 offset:2376
	ds_write_b32 v5, v94 offset:2640
	ds_write_b32 v5, v95 offset:2904
	ds_write_b32 v5, v96 offset:3168
	ds_write_b32 v5, v97 offset:3432
	ds_write_b32 v5, v98 offset:3696
	ds_write_b32 v5, v99 offset:3960
	ds_write_b32 v5, v100 offset:4224
	ds_write_b32 v5, v101 offset:4488
	ds_write_b32 v5, v102 offset:4752
	ds_write_b32 v5, v103 offset:5016
	ds_write_b32 v5, v104 offset:5280
	ds_write_b32 v5, v105 offset:5544
	ds_write_b32 v5, v106 offset:5808
	ds_write_b32 v5, v107 offset:6072
	ds_write_b32 v5, v108 offset:6336
	ds_write_b32 v5, v109 offset:6600
	ds_write_b32 v5, v110 offset:6864
	ds_write_b32 v5, v111 offset:7128
	ds_write_b32 v5, v112 offset:7392
	ds_write_b32 v5, v113 offset:7656
	ds_write_b32 v5, v114 offset:7920
	ds_write_b32 v5, v115 offset:8184
	v_add_u32_e32 v5, 0x2100, v5
	s_mov_b32 s5, 64
	s_branch .LBB0_103
